# LayerNorm row loops: counted vmcnt so the previous row stores stay in flight
# baseline (speedup 1.0000x reference)
.LBB0_337:
	s_and_b64 vcc, exec, s[4:5]
	s_cbranch_vccz .LBB0_367
	v_readlane_b32 s4, v255, 36
	s_add_u32 s4, s94, s4
	s_addc_u32 s5, s95, 0
	s_load_dwordx2 s[4:5], s[4:5], 0x0
	v_readlane_b32 s6, v255, 48
	s_waitcnt lgkmcnt(0)
	s_add_u32 s28, s4, s6
	s_addc_u32 s29, s5, 0
	v_readlane_b32 s4, v255, 37
	s_add_u32 s4, s94, s4
	s_addc_u32 s5, s95, 0
	s_load_dwordx2 s[4:5], s[4:5], 0x0
	s_waitcnt lgkmcnt(0)
	s_add_u32 s38, s4, s6
	s_addc_u32 s39, s5, 0
	s_cmp_gt_i32 s96, 16
	s_mov_b64 s[4:5], -1
	s_cbranch_scc0 .LBB0_347
	v_mov_b32_e32 v49, v216
	v_readlane_b32 s4, v253, 17
	v_ashrrev_i32_e32 v48, 6, v49
	s_nop 0
	v_add_u32_e32 v64, s4, v48
	v_cmp_gt_i32_e32 vcc, s18, v64
	s_and_saveexec_b64 s[8:9], vcc
	s_cbranch_execz .LBB0_346
	v_lshlrev_b32_e32 v0, 4, v49
	v_and_b32_e32 v192, 0x3f0, v0
	global_load_dwordx4 v[0:3], v192, s[28:29]
	global_load_dwordx4 v[4:7], v192, s[28:29] offset:1024
	global_load_dwordx4 v[8:11], v192, s[38:39]
	global_load_dwordx4 v[12:15], v192, s[38:39] offset:1024
	global_load_dwordx4 v[16:19], v192, s[28:29] offset:2048
	global_load_dwordx4 v[20:23], v192, s[28:29] offset:3072
	global_load_dwordx4 v[24:27], v192, s[38:39] offset:2048
	global_load_dwordx4 v[28:31], v192, s[38:39] offset:3072
	v_ashrrev_i32_e32 v65, 31, v64
	v_readlane_b32 s6, v254, 17
	v_lshlrev_b64 v[32:33], 12, v[64:65]
	v_readlane_b32 s7, v254, 18
	v_readlane_b32 s4, v253, 18
	v_xor_b32_e32 v50, 16, v221
	v_lshl_add_u64 v[66:67], s[6:7], 0, v[32:33]
	v_lshl_add_u64 v[32:33], v[66:67], 0, v[192:193]
	global_load_dwordx4 v[44:47], v[32:33], off
	global_load_dwordx4 v[40:43], v[32:33], off offset:1024
	global_load_dwordx4 v[36:39], v[32:33], off offset:2048
	s_nop 0
	global_load_dwordx4 v[32:35], v[32:33], off offset:3072
	v_add_u32_e32 v51, 64, v222
	v_and_b32_e32 v49, 63, v49
	v_add_u32_e32 v48, s4, v48
	v_cmp_lt_i32_e32 vcc, v50, v51
	v_lshlrev_b32_e32 v192, 4, v49
	v_ashrrev_i32_e32 v49, 31, v48
	v_cndmask_b32_e32 v50, v221, v50, vcc
	v_lshlrev_b64 v[48:49], 12, v[48:49]
	v_lshlrev_b32_e32 v65, 2, v50
	v_lshl_add_u64 v[68:69], s[6:7], 0, v[48:49]
	s_mov_b64 s[40:41], 0
	s_waitcnt vmcnt(0)
	s_branch .LBB0_342
.Lln17_nostore:
	s_waitcnt vmcnt(0)
	s_branch .LBB0_341
.LBB0_341:
	s_and_b64 s[4:5], exec, s[4:5]
	s_or_b64 s[40:41], s[4:5], s[40:41]
	v_readlane_b32 s4, v253, 36
	v_readlane_b32 s5, v253, 37
	s_waitcnt vmcnt(7)
	v_mov_b32_e32 v44, v48
	v_mov_b32_e32 v45, v49
	v_lshl_add_u64 v[66:67], v[66:67], 0, s[4:5]
	v_lshl_add_u64 v[68:69], v[68:69], 0, s[4:5]
	v_mov_b32_e32 v46, v50
	v_mov_b32_e32 v47, v51
	s_waitcnt vmcnt(6)
	v_mov_b32_e32 v40, v52
	v_mov_b32_e32 v41, v53
	v_mov_b32_e32 v42, v54
	v_mov_b32_e32 v43, v55
	s_waitcnt vmcnt(5)
	v_mov_b32_e32 v36, v56
	v_mov_b32_e32 v37, v57
	v_mov_b32_e32 v38, v58
	v_mov_b32_e32 v39, v59
	s_waitcnt vmcnt(4)
	v_mov_b32_e32 v32, v60
	v_mov_b32_e32 v33, v61
	v_mov_b32_e32 v34, v62
	v_mov_b32_e32 v35, v63
	s_andn2_b64 exec, exec, s[40:41]
	s_cbranch_execz .LBB0_346
.LBB0_342:
	v_add_u32_e32 v64, s54, v64
	v_cmp_gt_i32_e32 vcc, s18, v64
	v_cmp_lt_i32_e64 s[4:5], s34, v64
	s_waitcnt vmcnt(4)
	v_mov_b32_e32 v48, v44
	v_mov_b32_e32 v49, v45
	v_mov_b32_e32 v50, v46
	v_mov_b32_e32 v51, v47
	v_mov_b32_e32 v52, v40
	v_mov_b32_e32 v53, v41
	v_mov_b32_e32 v54, v42
	v_mov_b32_e32 v55, v43
	v_mov_b32_e32 v56, v36
	v_mov_b32_e32 v57, v37
	v_mov_b32_e32 v58, v38
	v_mov_b32_e32 v59, v39
	v_mov_b32_e32 v60, v32
	v_mov_b32_e32 v61, v33
	v_mov_b32_e32 v62, v34
	v_mov_b32_e32 v63, v35
	s_and_saveexec_b64 s[6:7], vcc
	s_cbranch_execz .LBB0_344
	v_lshl_add_u64 v[60:61], v[68:69], 0, v[192:193]
	global_load_dwordx4 v[48:51], v[60:61], off
	global_load_dwordx4 v[52:55], v[60:61], off offset:1024
	global_load_dwordx4 v[56:59], v[60:61], off offset:2048
	s_nop 0
	global_load_dwordx4 v[60:63], v[60:61], off offset:3072

.LBB0_347:
	s_andn2_b64 vcc, exec, s[4:5]
	s_cbranch_vccnz .LBB0_367
	s_cmp_lg_u32 s96, 9
	s_mov_b64 s[4:5], -1
	s_cbranch_scc0 .LBB0_357
	v_mov_b32_e32 v0, v216
	v_readlane_b32 s4, v253, 17
	v_ashrrev_i32_e32 v1, 6, v0
	s_nop 0
	v_add_u32_e32 v64, s4, v1
	v_cmp_gt_i32_e32 vcc, s18, v64
	s_and_saveexec_b64 s[40:41], vcc
	s_cbranch_execz .LBB0_356
	v_and_b32_e32 v48, 63, v0
	v_lshlrev_b32_e32 v192, 4, v48
	global_load_dwordx4 v[0:3], v192, s[28:29]
	global_load_dwordx4 v[4:7], v192, s[28:29] offset:1024
	global_load_dwordx4 v[8:11], v192, s[38:39]
	global_load_dwordx4 v[12:15], v192, s[38:39] offset:1024
	global_load_dwordx4 v[16:19], v192, s[28:29] offset:2048
	global_load_dwordx4 v[20:23], v192, s[28:29] offset:3072
	global_load_dwordx4 v[24:27], v192, s[38:39] offset:2048
	global_load_dwordx4 v[28:31], v192, s[38:39] offset:3072
	v_ashrrev_i32_e32 v65, 31, v64
	v_readlane_b32 s4, v254, 17
	v_lshlrev_b64 v[32:33], 12, v[64:65]
	v_readlane_b32 s5, v254, 18
	v_xor_b32_e32 v49, 16, v221
	v_add_u32_e32 v50, 64, v222
	v_lshl_add_u64 v[32:33], s[4:5], 0, v[32:33]
	v_lshl_add_u64 v[32:33], v[32:33], 0, v[192:193]
	global_load_dwordx4 v[44:47], v[32:33], off
	global_load_dwordx4 v[40:43], v[32:33], off offset:1024
	global_load_dwordx4 v[36:39], v[32:33], off offset:2048
	s_nop 0
	global_load_dwordx4 v[32:35], v[32:33], off offset:3072
	v_cmp_lt_i32_e32 vcc, v49, v50
	v_mov_b64_e32 v[50:51], 0x3900000
	v_lshlrev_b64 v[70:71], 11, v[64:65]
	v_cndmask_b32_e32 v49, v221, v49, vcc
	v_lshl_add_u64 v[66:67], s[4:5], 0, v[192:193]
	v_lshlrev_b32_e32 v73, 2, v49
	v_cmp_eq_u32_e64 s[4:5], 0, v48
	v_lshl_add_u64 v[68:69], v[64:65], 3, v[50:51]
	v_lshl_or_b32 v70, v48, 3, v70
	s_mov_b64 s[42:43], 0
	s_waitcnt vmcnt(0)
	s_branch .LBB0_352

.LBB0_352:
	v_add_u32_e32 v64, s54, v64
	v_cmp_gt_i32_e32 vcc, s18, v64
	v_cmp_lt_i32_e64 s[6:7], s34, v64
	s_waitcnt vmcnt(4)
	v_mov_b32_e32 v48, v44
	v_mov_b32_e32 v49, v45
	v_mov_b32_e32 v50, v46
	v_mov_b32_e32 v51, v47
	v_mov_b32_e32 v52, v40
	v_mov_b32_e32 v53, v41
	v_mov_b32_e32 v54, v42
	v_mov_b32_e32 v55, v43
	v_mov_b32_e32 v56, v36
	v_mov_b32_e32 v57, v37
	v_mov_b32_e32 v58, v38
	v_mov_b32_e32 v59, v39
	v_mov_b32_e32 v60, v32
	v_mov_b32_e32 v61, v33
	v_mov_b32_e32 v62, v34
	v_mov_b32_e32 v63, v35
	s_and_saveexec_b64 s[8:9], vcc
	s_cbranch_execz .LBB0_354
	v_ashrrev_i32_e32 v65, 31, v64
	v_lshlrev_b64 v[48:49], 12, v[64:65]
	v_lshl_add_u64 v[60:61], v[66:67], 0, v[48:49]
	global_load_dwordx4 v[48:51], v[60:61], off
	global_load_dwordx4 v[52:55], v[60:61], off offset:1024
	global_load_dwordx4 v[56:59], v[60:61], off offset:2048
	s_nop 0
	global_load_dwordx4 v[60:63], v[60:61], off offset:3072
